# attention loop: merged recentre check, V reads behind the compare, K fragments of the next QK prefetched during PV
# speedup vs baseline: 1.0332x; 1.0062x over previous
.Latt_h168:
	v_lshl_add_u32 v8, s10, 14, v214
	v_add_u32_e32 v38, v8, v217
	v_add_u32_e32 v39, v8, v218
	v_add_u32_e32 v40, v8, v219
	s_lshl_b32 s27, s10, 13
	s_and_b64 vcc, exec, s[4:5]
	s_cbranch_vccz .Latt_main
	s_cmp_eq_u32 s11, 0
	s_cbranch_scc1 .Latt_main
	s_add_i32 s2, s27, 0xffffe000
	s_cmp_lg_u32 s10, 0
	s_cselect_b32 s2, s2, 0xa000
	v_add_u32_e32 v8, s2, v210
	v_add_u32_e32 v42, v8, v215
	v_add_u32_e32 v43, v8, v216
	v_max3_f32 v36, v140, v141, v142
	v_max3_f32 v37, v124, v125, v126
	v_max3_f32 v36, v36, v143, v144
	v_max3_f32 v37, v37, v127, v128
	v_max3_f32 v36, v36, v145, v146
	v_max3_f32 v37, v37, v129, v130
	v_max3_f32 v36, v36, v147, v148
	v_max3_f32 v37, v37, v131, v132
	v_max3_f32 v36, v36, v149, v150
	v_max3_f32 v37, v37, v133, v134
	v_max3_f32 v36, v36, v151, v152
	v_max3_f32 v37, v37, v135, v136
	v_max3_f32 v36, v36, v153, v154
	v_max3_f32 v37, v37, v137, v138
	v_max3_f32 v36, v36, v155, v155
	v_max3_f32 v37, v37, v139, v139
	v_max_f32_e32 v9, v36, v37
	v_cmp_lt_f32_e32 vcc, s44, v9
	ds_read_b128 v[16:19], v42 offset:0
	ds_read_b128 v[20:23], v42 offset:2048
	ds_read_b128 v[24:27], v42 offset:4096
	ds_read_b128 v[28:31], v42 offset:6144
	ds_read_b128 v[188:191], v43 offset:0
	ds_read_b128 v[192:195], v43 offset:2048
	ds_read_b128 v[196:199], v43 offset:4096
	ds_read_b128 v[32:35], v43 offset:6144
	s_cbranch_vccnz .Latt_rare_p
.Latt_c_p:
	v_exp_f32_e32 v140, v140
	v_exp_f32_e32 v141, v141
	v_exp_f32_e32 v142, v142
	v_exp_f32_e32 v143, v143
	v_exp_f32_e32 v144, v144
	v_exp_f32_e32 v145, v145
	v_exp_f32_e32 v146, v146
	v_exp_f32_e32 v147, v147
	v_exp_f32_e32 v124, v124
	v_exp_f32_e32 v125, v125
	v_exp_f32_e32 v126, v126
	v_exp_f32_e32 v127, v127
	v_exp_f32_e32 v128, v128
	v_exp_f32_e32 v129, v129
	v_exp_f32_e32 v130, v130
	v_exp_f32_e32 v131, v131
	v_cvt_pk_bf16_f32 v140, v140, v141
	v_cvt_pk_bf16_f32 v141, v142, v143
	v_cvt_pk_bf16_f32 v142, v144, v145
	v_cvt_pk_bf16_f32 v143, v146, v147
	v_cvt_pk_bf16_f32 v124, v124, v125
	v_cvt_pk_bf16_f32 v125, v126, v127
	v_cvt_pk_bf16_f32 v126, v128, v129
	v_cvt_pk_bf16_f32 v127, v130, v131
	s_waitcnt lgkmcnt(4)
	ds_read_b128 v[156:159], v38 offset:0
	ds_read_b128 v[160:163], v38 offset:4096
	ds_read_b128 v[164:167], v38 offset:8192
	ds_read_b128 v[168:171], v38 offset:12288
	ds_read_b128 v[172:175], v39 offset:0
	ds_read_b128 v[176:179], v39 offset:4096
	ds_read_b128 v[180:183], v39 offset:8192
	ds_read_b128 v[184:187], v39 offset:12288
	s_setprio 1
	s_waitcnt lgkmcnt(12)
	v_mfma_f32_16x16x32_bf16 v[92:95], v[16:19], v[140:143], v[92:95]
	v_exp_f32_e32 v148, v148
	v_exp_f32_e32 v149, v149
	v_mfma_f32_16x16x32_bf16 v[96:99], v[16:19], v[124:127], v[96:99]
	v_exp_f32_e32 v150, v150
	v_exp_f32_e32 v151, v151
	v_mfma_f32_16x16x32_bf16 v[100:103], v[20:23], v[140:143], v[100:103]
	v_exp_f32_e32 v152, v152
	v_exp_f32_e32 v153, v153
	v_mfma_f32_16x16x32_bf16 v[104:107], v[20:23], v[124:127], v[104:107]
	v_exp_f32_e32 v154, v154
	v_exp_f32_e32 v155, v155
	v_mfma_f32_16x16x32_bf16 v[108:111], v[24:27], v[140:143], v[108:111]
	v_cvt_pk_bf16_f32 v148, v148, v149
	v_cvt_pk_bf16_f32 v149, v150, v151
	v_mfma_f32_16x16x32_bf16 v[112:115], v[24:27], v[124:127], v[112:115]
	v_cvt_pk_bf16_f32 v150, v152, v153
	v_cvt_pk_bf16_f32 v151, v154, v155
	v_mfma_f32_16x16x32_bf16 v[116:119], v[28:31], v[140:143], v[116:119]
	v_exp_f32_e32 v132, v132
	v_exp_f32_e32 v133, v133
	v_mfma_f32_16x16x32_bf16 v[120:123], v[28:31], v[124:127], v[120:123]
	v_exp_f32_e32 v134, v134
	v_exp_f32_e32 v135, v135
	v_mfma_f32_16x16x32_bf16 v[0:3], v[222:225], v[140:143], v[0:3]
	v_exp_f32_e32 v136, v136
	v_exp_f32_e32 v137, v137
	v_mfma_f32_16x16x32_bf16 v[4:7], v[222:225], v[124:127], v[4:7]
	v_exp_f32_e32 v138, v138
	v_exp_f32_e32 v139, v139
	s_waitcnt lgkmcnt(8)
	v_mfma_f32_16x16x32_bf16 v[92:95], v[188:191], v[148:151], v[92:95]
	v_cvt_pk_bf16_f32 v132, v132, v133
	v_cvt_pk_bf16_f32 v133, v134, v135
	v_mfma_f32_16x16x32_bf16 v[100:103], v[192:195], v[148:151], v[100:103]
	v_cvt_pk_bf16_f32 v134, v136, v137
	v_cvt_pk_bf16_f32 v135, v138, v139
	v_mfma_f32_16x16x32_bf16 v[108:111], v[196:199], v[148:151], v[108:111]
	v_mfma_f32_16x16x32_bf16 v[116:119], v[32:35], v[148:151], v[116:119]
	v_mfma_f32_16x16x32_bf16 v[0:3], v[222:225], v[148:151], v[0:3]
	v_mfma_f32_16x16x32_bf16 v[96:99], v[188:191], v[132:135], v[96:99]
	v_mfma_f32_16x16x32_bf16 v[104:107], v[192:195], v[132:135], v[104:107]
	v_mfma_f32_16x16x32_bf16 v[112:115], v[196:199], v[132:135], v[112:115]
	v_mfma_f32_16x16x32_bf16 v[120:123], v[32:35], v[132:135], v[120:123]
	v_mfma_f32_16x16x32_bf16 v[4:7], v[222:225], v[132:135], v[4:7]
	s_setprio 0
	s_branch .Latt_qk0_pre

.Latt_qk0_pre:
	s_setprio 1
	s_waitcnt lgkmcnt(7)
	v_mfma_f32_16x16x32_bf16 v[140:143], v[156:159], v[44:47], v[226:229]
	v_mfma_f32_16x16x32_bf16 v[124:127], v[156:159], v[56:59], v[230:233]
	s_waitcnt lgkmcnt(6)
	v_mfma_f32_16x16x32_bf16 v[144:147], v[160:163], v[44:47], v[226:229]
	v_mfma_f32_16x16x32_bf16 v[128:131], v[160:163], v[56:59], v[230:233]
	s_waitcnt lgkmcnt(5)
	v_mfma_f32_16x16x32_bf16 v[148:151], v[164:167], v[44:47], v[226:229]
	v_mfma_f32_16x16x32_bf16 v[132:135], v[164:167], v[56:59], v[230:233]
	s_waitcnt lgkmcnt(4)
	v_mfma_f32_16x16x32_bf16 v[152:155], v[168:171], v[44:47], v[226:229]
	v_mfma_f32_16x16x32_bf16 v[136:139], v[168:171], v[56:59], v[230:233]
	s_waitcnt lgkmcnt(3)
	v_mfma_f32_16x16x32_bf16 v[140:143], v[172:175], v[48:51], v[140:143]
	v_mfma_f32_16x16x32_bf16 v[124:127], v[172:175], v[60:63], v[124:127]
	ds_read_b128 v[156:159], v40 offset:0
	ds_read_b128 v[160:163], v40 offset:4096
	ds_read_b128 v[164:167], v40 offset:8192
	ds_read_b128 v[168:171], v40 offset:12288
	s_waitcnt lgkmcnt(6)
	v_mfma_f32_16x16x32_bf16 v[144:147], v[176:179], v[48:51], v[144:147]
	v_mfma_f32_16x16x32_bf16 v[128:131], v[176:179], v[60:63], v[128:131]
	s_waitcnt lgkmcnt(5)
	v_mfma_f32_16x16x32_bf16 v[148:151], v[180:183], v[48:51], v[148:151]
	v_mfma_f32_16x16x32_bf16 v[132:135], v[180:183], v[60:63], v[132:135]
	s_waitcnt lgkmcnt(4)
	v_mfma_f32_16x16x32_bf16 v[152:155], v[184:187], v[48:51], v[152:155]
	v_mfma_f32_16x16x32_bf16 v[136:139], v[184:187], v[60:63], v[136:139]
	s_waitcnt lgkmcnt(3)
	v_mfma_f32_16x16x32_bf16 v[140:143], v[156:159], v[52:55], v[140:143]
	v_mfma_f32_16x16x32_bf16 v[124:127], v[156:159], v[64:67], v[124:127]
	s_waitcnt lgkmcnt(2)
	v_mfma_f32_16x16x32_bf16 v[144:147], v[160:163], v[52:55], v[144:147]
	v_mfma_f32_16x16x32_bf16 v[128:131], v[160:163], v[64:67], v[128:131]
	s_waitcnt lgkmcnt(1)
	v_mfma_f32_16x16x32_bf16 v[148:151], v[164:167], v[52:55], v[148:151]
	v_mfma_f32_16x16x32_bf16 v[132:135], v[164:167], v[64:67], v[132:135]
	s_waitcnt lgkmcnt(0)
	v_mfma_f32_16x16x32_bf16 v[152:155], v[168:171], v[52:55], v[152:155]
	v_mfma_f32_16x16x32_bf16 v[136:139], v[168:171], v[64:67], v[136:139]
	s_setprio 0
	v_add_u32_e32 v8, s27, v210
	v_add_u32_e32 v42, v8, v215
	v_add_u32_e32 v43, v8, v216
	v_max3_f32 v36, v140, v141, v142
	v_max3_f32 v37, v124, v125, v126
	v_max3_f32 v36, v36, v143, v144
	v_max3_f32 v37, v37, v127, v128
	v_max3_f32 v36, v36, v145, v146
	v_max3_f32 v37, v37, v129, v130
	v_max3_f32 v36, v36, v147, v148
	v_max3_f32 v37, v37, v131, v132
	v_max3_f32 v36, v36, v149, v150
	v_max3_f32 v37, v37, v133, v134
	v_max3_f32 v36, v36, v151, v152
	v_max3_f32 v37, v37, v135, v136
	v_max3_f32 v36, v36, v153, v154
	v_max3_f32 v37, v37, v137, v138
	v_max3_f32 v36, v36, v155, v155
	v_max3_f32 v37, v37, v139, v139
	v_max_f32_e32 v9, v36, v37
	v_cmp_lt_f32_e32 vcc, s44, v9
	ds_read_b128 v[16:19], v42 offset:0
	ds_read_b128 v[20:23], v42 offset:2048
	ds_read_b128 v[24:27], v42 offset:4096
	ds_read_b128 v[28:31], v42 offset:6144
	ds_read_b128 v[188:191], v43 offset:0
	ds_read_b128 v[192:195], v43 offset:2048
	ds_read_b128 v[196:199], v43 offset:4096
	ds_read_b128 v[32:35], v43 offset:6144
	s_cmp_eq_u32 s11, 0
	s_cbranch_scc1 .Latt_rare_a
	s_cbranch_vccnz .Latt_rare_a
.Latt_c_a:
	v_exp_f32_e32 v140, v140
	v_exp_f32_e32 v141, v141
	v_exp_f32_e32 v142, v142
	v_exp_f32_e32 v143, v143
	v_exp_f32_e32 v144, v144
	v_exp_f32_e32 v145, v145
	v_exp_f32_e32 v146, v146
	v_exp_f32_e32 v147, v147
	v_exp_f32_e32 v124, v124
	v_exp_f32_e32 v125, v125
	v_exp_f32_e32 v126, v126
	v_exp_f32_e32 v127, v127
	v_exp_f32_e32 v128, v128
	v_exp_f32_e32 v129, v129
	v_exp_f32_e32 v130, v130
	v_exp_f32_e32 v131, v131
	v_cvt_pk_bf16_f32 v140, v140, v141
	v_cvt_pk_bf16_f32 v141, v142, v143
	v_cvt_pk_bf16_f32 v142, v144, v145
	v_cvt_pk_bf16_f32 v143, v146, v147
	v_cvt_pk_bf16_f32 v124, v124, v125
	v_cvt_pk_bf16_f32 v125, v126, v127
	v_cvt_pk_bf16_f32 v126, v128, v129
	v_cvt_pk_bf16_f32 v127, v130, v131
	s_waitcnt lgkmcnt(4)
	ds_read_b128 v[156:159], v38 offset:16384
	ds_read_b128 v[160:163], v38 offset:20480
	ds_read_b128 v[164:167], v38 offset:24576
	ds_read_b128 v[168:171], v38 offset:28672
	ds_read_b128 v[172:175], v39 offset:16384
	ds_read_b128 v[176:179], v39 offset:20480
	ds_read_b128 v[180:183], v39 offset:24576
	ds_read_b128 v[184:187], v39 offset:28672
	s_setprio 1
	s_waitcnt lgkmcnt(12)
	v_mfma_f32_16x16x32_bf16 v[92:95], v[16:19], v[140:143], v[92:95]
	v_exp_f32_e32 v148, v148
	v_exp_f32_e32 v149, v149
	v_mfma_f32_16x16x32_bf16 v[96:99], v[16:19], v[124:127], v[96:99]
	v_exp_f32_e32 v150, v150
	v_exp_f32_e32 v151, v151
	v_mfma_f32_16x16x32_bf16 v[100:103], v[20:23], v[140:143], v[100:103]
	v_exp_f32_e32 v152, v152
	v_exp_f32_e32 v153, v153
	v_mfma_f32_16x16x32_bf16 v[104:107], v[20:23], v[124:127], v[104:107]
	v_exp_f32_e32 v154, v154
	v_exp_f32_e32 v155, v155
	v_mfma_f32_16x16x32_bf16 v[108:111], v[24:27], v[140:143], v[108:111]
	v_cvt_pk_bf16_f32 v148, v148, v149
	v_cvt_pk_bf16_f32 v149, v150, v151
	v_mfma_f32_16x16x32_bf16 v[112:115], v[24:27], v[124:127], v[112:115]
	v_cvt_pk_bf16_f32 v150, v152, v153
	v_cvt_pk_bf16_f32 v151, v154, v155
	v_mfma_f32_16x16x32_bf16 v[116:119], v[28:31], v[140:143], v[116:119]
	v_exp_f32_e32 v132, v132
	v_exp_f32_e32 v133, v133
	v_mfma_f32_16x16x32_bf16 v[120:123], v[28:31], v[124:127], v[120:123]
	v_exp_f32_e32 v134, v134
	v_exp_f32_e32 v135, v135
	v_mfma_f32_16x16x32_bf16 v[0:3], v[222:225], v[140:143], v[0:3]
	v_exp_f32_e32 v136, v136
	v_exp_f32_e32 v137, v137
	v_mfma_f32_16x16x32_bf16 v[4:7], v[222:225], v[124:127], v[4:7]
	v_exp_f32_e32 v138, v138
	v_exp_f32_e32 v139, v139
	s_waitcnt lgkmcnt(8)
	v_mfma_f32_16x16x32_bf16 v[92:95], v[188:191], v[148:151], v[92:95]
	v_cvt_pk_bf16_f32 v132, v132, v133
	v_cvt_pk_bf16_f32 v133, v134, v135
	v_mfma_f32_16x16x32_bf16 v[100:103], v[192:195], v[148:151], v[100:103]
	v_cvt_pk_bf16_f32 v134, v136, v137
	v_cvt_pk_bf16_f32 v135, v138, v139
	v_mfma_f32_16x16x32_bf16 v[108:111], v[196:199], v[148:151], v[108:111]
	v_mfma_f32_16x16x32_bf16 v[116:119], v[32:35], v[148:151], v[116:119]
	v_mfma_f32_16x16x32_bf16 v[0:3], v[222:225], v[148:151], v[0:3]
	v_mfma_f32_16x16x32_bf16 v[96:99], v[188:191], v[132:135], v[96:99]
	v_mfma_f32_16x16x32_bf16 v[104:107], v[192:195], v[132:135], v[104:107]
	v_mfma_f32_16x16x32_bf16 v[112:115], v[196:199], v[132:135], v[112:115]
	v_mfma_f32_16x16x32_bf16 v[120:123], v[32:35], v[132:135], v[120:123]
	v_mfma_f32_16x16x32_bf16 v[4:7], v[222:225], v[132:135], v[4:7]
	s_setprio 0
	s_setprio 1
	s_waitcnt lgkmcnt(7)
	v_mfma_f32_16x16x32_bf16 v[140:143], v[156:159], v[44:47], v[226:229]
	v_mfma_f32_16x16x32_bf16 v[124:127], v[156:159], v[56:59], v[230:233]
	s_waitcnt lgkmcnt(6)
	v_mfma_f32_16x16x32_bf16 v[144:147], v[160:163], v[44:47], v[226:229]
	v_mfma_f32_16x16x32_bf16 v[128:131], v[160:163], v[56:59], v[230:233]
	s_waitcnt lgkmcnt(5)
	v_mfma_f32_16x16x32_bf16 v[148:151], v[164:167], v[44:47], v[226:229]
	v_mfma_f32_16x16x32_bf16 v[132:135], v[164:167], v[56:59], v[230:233]
	s_waitcnt lgkmcnt(4)
	v_mfma_f32_16x16x32_bf16 v[152:155], v[168:171], v[44:47], v[226:229]
	v_mfma_f32_16x16x32_bf16 v[136:139], v[168:171], v[56:59], v[230:233]
	s_waitcnt lgkmcnt(3)
	v_mfma_f32_16x16x32_bf16 v[140:143], v[172:175], v[48:51], v[140:143]
	v_mfma_f32_16x16x32_bf16 v[124:127], v[172:175], v[60:63], v[124:127]
	ds_read_b128 v[156:159], v40 offset:16384
	ds_read_b128 v[160:163], v40 offset:20480
	ds_read_b128 v[164:167], v40 offset:24576
	ds_read_b128 v[168:171], v40 offset:28672
	s_waitcnt lgkmcnt(6)
	v_mfma_f32_16x16x32_bf16 v[144:147], v[176:179], v[48:51], v[144:147]
	v_mfma_f32_16x16x32_bf16 v[128:131], v[176:179], v[60:63], v[128:131]
	s_waitcnt lgkmcnt(5)
	v_mfma_f32_16x16x32_bf16 v[148:151], v[180:183], v[48:51], v[148:151]
	v_mfma_f32_16x16x32_bf16 v[132:135], v[180:183], v[60:63], v[132:135]
	s_waitcnt lgkmcnt(4)
	v_mfma_f32_16x16x32_bf16 v[152:155], v[184:187], v[48:51], v[152:155]
	v_mfma_f32_16x16x32_bf16 v[136:139], v[184:187], v[60:63], v[136:139]
	s_waitcnt lgkmcnt(3)
	v_mfma_f32_16x16x32_bf16 v[140:143], v[156:159], v[52:55], v[140:143]
	v_mfma_f32_16x16x32_bf16 v[124:127], v[156:159], v[64:67], v[124:127]
	s_waitcnt lgkmcnt(2)
	v_mfma_f32_16x16x32_bf16 v[144:147], v[160:163], v[52:55], v[144:147]
	v_mfma_f32_16x16x32_bf16 v[128:131], v[160:163], v[64:67], v[128:131]
	s_waitcnt lgkmcnt(1)
	v_mfma_f32_16x16x32_bf16 v[148:151], v[164:167], v[52:55], v[148:151]
	v_mfma_f32_16x16x32_bf16 v[132:135], v[164:167], v[64:67], v[132:135]
	s_waitcnt lgkmcnt(0)
	v_mfma_f32_16x16x32_bf16 v[152:155], v[168:171], v[52:55], v[152:155]
	v_mfma_f32_16x16x32_bf16 v[136:139], v[168:171], v[64:67], v[136:139]
	s_setprio 0
	s_and_b64 vcc, exec, s[4:5]
	s_cbranch_vccnz .Latt_tail
	v_max3_f32 v36, v140, v141, v142
	v_max3_f32 v37, v124, v125, v126
	v_max3_f32 v36, v36, v143, v144
	v_max3_f32 v37, v37, v127, v128
	v_max3_f32 v36, v36, v145, v146
	v_max3_f32 v37, v37, v129, v130
	v_max3_f32 v36, v36, v147, v148
	v_max3_f32 v37, v37, v131, v132
	v_max3_f32 v36, v36, v149, v150
	v_max3_f32 v37, v37, v133, v134
	v_max3_f32 v36, v36, v151, v152
	v_max3_f32 v37, v37, v135, v136
	v_max3_f32 v36, v36, v153, v154
	v_max3_f32 v37, v37, v137, v138
	v_max3_f32 v36, v36, v155, v155
	v_max3_f32 v37, v37, v139, v139
	v_max_f32_e32 v9, v36, v37
	v_cmp_lt_f32_e32 vcc, s44, v9
	ds_read_b128 v[16:19], v42 offset:8192
	ds_read_b128 v[20:23], v42 offset:10240
	ds_read_b128 v[24:27], v42 offset:12288
	ds_read_b128 v[28:31], v42 offset:14336
	ds_read_b128 v[188:191], v43 offset:8192
	ds_read_b128 v[192:195], v43 offset:10240
	ds_read_b128 v[196:199], v43 offset:12288
	ds_read_b128 v[32:35], v43 offset:14336
	s_cbranch_vccnz .Latt_rare_b

.Latt_rare_p:
	v_cmp_lt_f32_e32 vcc, s44, v36
	s_cbranch_vccz .Latt_r1chk_p

.Latt_r1chk_p:
	v_cmp_lt_f32_e32 vcc, s44, v37
	s_cbranch_vccz .Latt_c_p

.Latt_rare_a:
	s_cmp_eq_u32 s11, 0
	s_cbranch_scc1 .Latt_r0_a
	v_cmp_lt_f32_e32 vcc, s44, v36
	s_cbranch_vccz .Latt_r1chk_a

.Latt_r1chk_a:
	s_cmp_eq_u32 s11, 0
	s_cbranch_scc1 .Latt_r1_a
	v_cmp_lt_f32_e32 vcc, s44, v37
	s_cbranch_vccz .Latt_c_a
